# ffn1: tile-queue atomic for the next pull issued at epilogue start (thread 0), consumed at next tile top
# speedup vs baseline: 1.0440x; 1.0027x over previous
.LBB0_3:
	s_or_b64 exec, exec, s[4:5]
	v_readlane_b32 s6, v255, 0
	s_cmpk_lt_i32 s6, 0x1800
	s_cselect_b64 s[4:5], -1, 0
	v_writelane_b32 v255, s4, 3
	s_mov_b32 s19, s27
	s_lshl_b32 s7, s6, 2
	v_writelane_b32 v255, s5, 4
	s_waitcnt lgkmcnt(0)
	s_lshl_b64 s[4:5], s[18:19], 14
	v_writelane_b32 v255, s4, 5
	s_and_b32 s2, s18, 7
	v_lshrrev_b32_e32 v1, 20, v0
	v_writelane_b32 v255, s5, 6
	s_and_b32 s4, s6, 7
	s_ashr_i32 s5, s18, 3
	s_mul_i32 s4, s5, s4
	s_ashr_i32 s5, s6, 3
	s_add_i32 s4, s4, s5
	s_cmpk_lt_i32 s6, 0x80
	s_cselect_b64 s[8:9], -1, 0
	v_writelane_b32 v255, s8, 7
	s_cmpk_lt_i32 s6, 0x1760
	v_lshrrev_b32_e32 v0, 10, v0
	v_writelane_b32 v255, s9, 8
	s_cselect_b64 s[8:9], -1, 0
	v_writelane_b32 v255, s8, 9
	s_cmpk_lt_i32 s6, 0x1160
	v_or_b32_e32 v0, v0, v1
	v_writelane_b32 v255, s9, 10
	s_cselect_b64 s[8:9], -1, 0
	v_writelane_b32 v255, s8, 11
	s_cmpk_lt_i32 s6, 0xc0
	v_and_or_b32 v0, v0, s3, v254
	v_writelane_b32 v255, s9, 12
	s_cselect_b64 s[8:9], -1, 0
	v_writelane_b32 v255, s8, 13
	s_cmp_eq_u32 s2, 0
	s_cselect_b32 s2, s4, s6
	v_writelane_b32 v255, s9, 14
	v_cmp_eq_u32_e64 s[8:9], 0, v0
	s_cmpk_lt_i32 s2, 0x600
	s_cselect_b64 s[4:5], -1, 0
	v_writelane_b32 v255, s8, 15
	s_lshl_b32 s90, s18, 2
	s_lshl_b32 s91, s18, 6
	v_writelane_b32 v255, s9, 16
	v_writelane_b32 v255, s2, 17
	v_writelane_b32 v255, s4, 18
	s_lshl_b32 s2, s6, 6
	s_movk_i32 s89, 0x1800
	v_writelane_b32 v255, s5, 19
	v_writelane_b32 v255, s2, 20
	s_lshl_b32 s2, s6, 12
	s_add_i32 s2, s2, 0xfeeb0000
	v_writelane_b32 v255, s2, 21
	s_lshl_b32 s2, s18, 12
	v_writelane_b32 v255, s2, 22
	v_writelane_b32 v255, s7, 23
	s_add_i32 s2, s7, 0x3cb80
	v_writelane_b32 v255, s2, 24
	v_writelane_b32 v255, s90, 25
	s_movk_i32 s55, 0xc0
	s_movk_i32 s24, 0x600
	v_mov_b32_e32 v149, 0
	s_movk_i32 s92, 0x300
	s_mov_b32 s57, 0x800000
	s_movk_i32 s34, 0x1fff
	s_movk_i32 s35, 0x6000
	s_movk_i32 s93, 0x104
	v_mov_b32_e32 v159, 1
	v_mov_b32_e32 v158, 0x11ff0
	s_mov_b32 s47, 0x1ffffc0
	s_mov_b64 s[50:51], 0x1201080
	s_movk_i32 s48, 0x210
	s_mov_b32 s49, 0xfffffc0
	s_movk_i32 s42, 0x110
	s_movk_i32 s43, 0xc00
	s_movk_i32 s98, 0x90
	s_mov_b32 s38, 0xf149f2ca
	s_mov_b32 s39, 0x5040100
	s_movk_i32 s19, 0x1400
	s_movk_i32 s96, 0x2b8
	s_movk_i32 s97, 0x15c0
	s_mov_b32 s25, 0
	s_mov_b64 s[52:53], 0x80
	s_mov_b32 s54, 0x3fb504f3
	s_mov_b64 s[58:59], 0x10000
	s_mov_b64 s[60:61], 0x20000
	s_mov_b64 s[62:63], 0x30000
	s_mov_b64 s[64:65], 0xe0c1080
	s_mov_b64 s[66:67], 0xe0d1080
	s_mov_b64 s[68:69], 0xe0e1080
	s_mov_b64 s[70:71], 0xe0f1080
	s_mov_b64 s[72:73], 0x2000
	s_mov_b64 s[74:75], 0x8000
	s_mov_b64 s[76:77], 0x18000
	s_mov_b64 s[78:79], 0xf8c0f00
	s_mov_b64 s[80:81], 0x2dc1400
	v_writelane_b32 v255, s91, 26
	s_mov_b32 s100, 0
	s_barrier
	s_branch .LBB0_5

.LBB0_177:
	v_mov_b32_e32 v64, v254
	s_waitcnt vmcnt(0)
	s_barrier
	s_and_saveexec_b64 s[14:15], s[4:5]
	s_cbranch_execz .Lpp1_skip
	v_cmp_gt_i32_e32 vcc, 8, v84
	s_and_b64 exec, exec, vcc
	s_cbranch_execz .Lpp1_skip
	v_add_u32_e32 v252, s2, v84
	v_and_b32_e32 v252, 7, v252
	v_lshlrev_b32_e32 v252, 6, v252
	global_atomic_add v253, v252, v159, s[12:13] sc0
	s_mov_b32 s100, 1
.Lpp1_skip:
	s_or_b64 exec, exec, s[14:15]
	s_nop 1
	v_max_f32_e32 v0, v0, v0
	v_lshrrev_b32_e32 v66, 2, v64
	v_lshrrev_b32_e32 v65, 1, v64
	v_and_b32_e32 v66, 12, v66
	v_and_or_b32 v65, v65, s49, v66
	v_max_f32_e32 v0, 0, v0
	v_and_b32_e32 v64, 0x4f, v64
	v_mul_lo_u32 v65, v65, s42
	v_mul_f32_e32 v0, v0, v0
	v_lshl_add_u32 v64, v64, 1, v65
	v_cvt_pk_bf16_f32 v0, v0, s0
	ds_write_b16 v64, v0 offset:45856
	v_max_f32_e32 v0, v1, v1
	v_max_f32_e32 v0, 0, v0
	v_mul_f32_e32 v0, v0, v0
	v_cvt_pk_bf16_f32 v0, v0, s0
	ds_write_b16 v64, v0 offset:46128
	v_max_f32_e32 v0, v2, v2
	v_max_f32_e32 v0, 0, v0
	v_mul_f32_e32 v0, v0, v0
	v_cvt_pk_bf16_f32 v0, v0, s0
	ds_write_b16 v64, v0 offset:46400
	v_max_f32_e32 v0, v3, v3
	v_max_f32_e32 v0, 0, v0
	v_mul_f32_e32 v0, v0, v0
	v_cvt_pk_bf16_f32 v0, v0, s0
	ds_write_b16 v64, v0 offset:46672
	v_max_f32_e32 v0, v12, v12
	v_max_f32_e32 v0, 0, v0
	v_mul_f32_e32 v0, v0, v0
	v_cvt_pk_bf16_f32 v0, v0, s0
	ds_write_b16 v64, v0 offset:45888
	v_max_f32_e32 v0, v13, v13
	v_max_f32_e32 v0, 0, v0
	v_mul_f32_e32 v0, v0, v0
	v_cvt_pk_bf16_f32 v0, v0, s0
	ds_write_b16 v64, v0 offset:46160
	v_max_f32_e32 v0, v14, v14
	v_max_f32_e32 v0, 0, v0
	v_mul_f32_e32 v0, v0, v0
	v_cvt_pk_bf16_f32 v0, v0, s0
	ds_write_b16 v64, v0 offset:46432
	v_max_f32_e32 v0, v15, v15
	v_max_f32_e32 v0, 0, v0
	v_mul_f32_e32 v0, v0, v0
	v_cvt_pk_bf16_f32 v0, v0, s0
	v_max_f32_e32 v60, v60, v60
	v_max_f32_e32 v56, v56, v56
	v_max_f32_e32 v52, v52, v52
	v_max_f32_e32 v48, v48, v48
	v_max_f32_e32 v44, v44, v44
	v_max_f32_e32 v40, v40, v40
	v_max_f32_e32 v36, v36, v36
	v_max_f32_e32 v32, v32, v32
	v_max_f32_e32 v28, v28, v28
	v_max_f32_e32 v24, v24, v24
	v_max_f32_e32 v20, v20, v20
	v_max_f32_e32 v16, v16, v16
	v_max_f32_e32 v8, v8, v8
	ds_write_b16 v64, v0 offset:46704
	v_max_f32_e32 v0, v4, v4
	v_max_f32_e32 v60, 0, v60
	v_max_f32_e32 v56, 0, v56
	v_max_f32_e32 v52, 0, v52
	v_max_f32_e32 v48, 0, v48
	v_max_f32_e32 v44, 0, v44
	v_max_f32_e32 v40, 0, v40
	v_max_f32_e32 v36, 0, v36
	v_max_f32_e32 v32, 0, v32
	v_max_f32_e32 v28, 0, v28
	v_max_f32_e32 v24, 0, v24
	v_max_f32_e32 v20, 0, v20
	v_max_f32_e32 v16, 0, v16
	v_max_f32_e32 v8, 0, v8
	v_max_f32_e32 v0, 0, v0
	v_mul_f32_e32 v60, v60, v60
	v_mul_f32_e32 v56, v56, v56
	v_mul_f32_e32 v52, v52, v52
	v_mul_f32_e32 v48, v48, v48
	v_mul_f32_e32 v44, v44, v44
	v_mul_f32_e32 v40, v40, v40
	v_mul_f32_e32 v36, v36, v36
	v_mul_f32_e32 v32, v32, v32
	v_mul_f32_e32 v28, v28, v28
	v_mul_f32_e32 v24, v24, v24
	v_mul_f32_e32 v20, v20, v20
	v_mul_f32_e32 v16, v16, v16
	v_mul_f32_e32 v8, v8, v8
	v_mul_f32_e32 v0, v0, v0
	v_cvt_pk_bf16_f32 v60, v60, s0
	v_cvt_pk_bf16_f32 v56, v56, s0
	v_cvt_pk_bf16_f32 v52, v52, s0
	v_cvt_pk_bf16_f32 v48, v48, s0
	v_cvt_pk_bf16_f32 v44, v44, s0
	v_cvt_pk_bf16_f32 v40, v40, s0
	v_cvt_pk_bf16_f32 v36, v36, s0
	v_cvt_pk_bf16_f32 v32, v32, s0
	v_cvt_pk_bf16_f32 v28, v28, s0
	v_cvt_pk_bf16_f32 v24, v24, s0
	v_cvt_pk_bf16_f32 v20, v20, s0
	v_cvt_pk_bf16_f32 v16, v16, s0
	v_cvt_pk_bf16_f32 v8, v8, s0
	v_cvt_pk_bf16_f32 v0, v0, s0
	ds_write_b16 v64, v60 offset:32768
	v_max_f32_e32 v60, v61, v61
	ds_write_b16 v64, v56 offset:32800
	v_max_f32_e32 v56, v57, v57
	ds_write_b16 v64, v52 offset:32832
	v_max_f32_e32 v52, v53, v53
	ds_write_b16 v64, v48 offset:32864
	v_max_f32_e32 v48, v49, v49
	ds_write_b16 v64, v44 offset:37120
	v_max_f32_e32 v44, v45, v45
	ds_write_b16 v64, v40 offset:37152
	v_max_f32_e32 v40, v41, v41
	ds_write_b16 v64, v36 offset:37184
	v_max_f32_e32 v36, v37, v37
	ds_write_b16 v64, v32 offset:37216
	v_max_f32_e32 v32, v33, v33
	ds_write_b16 v64, v28 offset:41472
	v_max_f32_e32 v28, v29, v29
	ds_write_b16 v64, v24 offset:41504
	v_max_f32_e32 v24, v25, v25
	ds_write_b16 v64, v20 offset:41536
	v_max_f32_e32 v20, v21, v21
	ds_write_b16 v64, v16 offset:41568
	v_max_f32_e32 v16, v17, v17
	ds_write_b16 v64, v8 offset:45824
	v_max_f32_e32 v8, v9, v9
	ds_write_b16 v64, v0 offset:45920
	v_max_f32_e32 v0, v5, v5
	v_max_f32_e32 v60, 0, v60
	v_max_f32_e32 v56, 0, v56
	v_max_f32_e32 v52, 0, v52
	v_max_f32_e32 v48, 0, v48
	v_max_f32_e32 v44, 0, v44
	v_max_f32_e32 v40, 0, v40
	v_max_f32_e32 v36, 0, v36
	v_max_f32_e32 v32, 0, v32
	v_max_f32_e32 v28, 0, v28
	v_max_f32_e32 v24, 0, v24
	v_max_f32_e32 v20, 0, v20
	v_max_f32_e32 v16, 0, v16
	v_max_f32_e32 v8, 0, v8
	v_max_f32_e32 v0, 0, v0
	v_mul_f32_e32 v60, v60, v60
	v_mul_f32_e32 v56, v56, v56
	v_mul_f32_e32 v52, v52, v52
	v_mul_f32_e32 v48, v48, v48
	v_mul_f32_e32 v44, v44, v44
	v_mul_f32_e32 v40, v40, v40
	v_mul_f32_e32 v36, v36, v36
	v_mul_f32_e32 v32, v32, v32
	v_mul_f32_e32 v28, v28, v28
	v_mul_f32_e32 v24, v24, v24
	v_mul_f32_e32 v20, v20, v20
	v_mul_f32_e32 v16, v16, v16
	v_mul_f32_e32 v8, v8, v8
	v_mul_f32_e32 v0, v0, v0
	v_cvt_pk_bf16_f32 v60, v60, s0
	v_cvt_pk_bf16_f32 v56, v56, s0
	v_cvt_pk_bf16_f32 v52, v52, s0
	v_cvt_pk_bf16_f32 v48, v48, s0
	v_cvt_pk_bf16_f32 v44, v44, s0
	v_cvt_pk_bf16_f32 v40, v40, s0
	v_cvt_pk_bf16_f32 v36, v36, s0
	v_cvt_pk_bf16_f32 v32, v32, s0
	v_cvt_pk_bf16_f32 v28, v28, s0
	v_cvt_pk_bf16_f32 v24, v24, s0
	v_cvt_pk_bf16_f32 v20, v20, s0
	v_cvt_pk_bf16_f32 v16, v16, s0
	v_cvt_pk_bf16_f32 v8, v8, s0
	v_cvt_pk_bf16_f32 v0, v0, s0
	ds_write_b16 v64, v60 offset:33040
	v_max_f32_e32 v60, v62, v62
	ds_write_b16 v64, v56 offset:33072
	v_max_f32_e32 v56, v58, v58
	ds_write_b16 v64, v52 offset:33104
	v_max_f32_e32 v52, v54, v54
	ds_write_b16 v64, v48 offset:33136
	v_max_f32_e32 v48, v50, v50
	ds_write_b16 v64, v44 offset:37392
	v_max_f32_e32 v44, v46, v46
	ds_write_b16 v64, v40 offset:37424
	v_max_f32_e32 v40, v42, v42
	ds_write_b16 v64, v36 offset:37456
	v_max_f32_e32 v36, v38, v38
	ds_write_b16 v64, v32 offset:37488
	v_max_f32_e32 v32, v34, v34
	ds_write_b16 v64, v28 offset:41744
	v_max_f32_e32 v28, v30, v30
	ds_write_b16 v64, v24 offset:41776
	v_max_f32_e32 v24, v26, v26
	ds_write_b16 v64, v20 offset:41808
	v_max_f32_e32 v20, v22, v22
	ds_write_b16 v64, v16 offset:41840
	v_max_f32_e32 v16, v18, v18
	ds_write_b16 v64, v8 offset:46096
	v_max_f32_e32 v8, v10, v10
	ds_write_b16 v64, v0 offset:46192
	v_max_f32_e32 v0, v6, v6
	v_max_f32_e32 v60, 0, v60
	v_max_f32_e32 v56, 0, v56
	v_max_f32_e32 v52, 0, v52
	v_max_f32_e32 v48, 0, v48
	v_max_f32_e32 v44, 0, v44
	v_max_f32_e32 v40, 0, v40
	v_max_f32_e32 v36, 0, v36
	v_max_f32_e32 v32, 0, v32
	v_max_f32_e32 v28, 0, v28
	v_max_f32_e32 v24, 0, v24
	v_max_f32_e32 v20, 0, v20
	v_max_f32_e32 v16, 0, v16
	v_max_f32_e32 v8, 0, v8
	v_max_f32_e32 v0, 0, v0
	v_mul_f32_e32 v60, v60, v60
	v_mul_f32_e32 v56, v56, v56
	v_mul_f32_e32 v52, v52, v52
	v_mul_f32_e32 v48, v48, v48
	v_mul_f32_e32 v44, v44, v44
	v_mul_f32_e32 v40, v40, v40
	v_mul_f32_e32 v36, v36, v36
	v_mul_f32_e32 v32, v32, v32
	v_mul_f32_e32 v28, v28, v28
	v_mul_f32_e32 v24, v24, v24
	v_mul_f32_e32 v20, v20, v20
	v_mul_f32_e32 v16, v16, v16
	v_mul_f32_e32 v8, v8, v8
	v_mul_f32_e32 v0, v0, v0
	v_cvt_pk_bf16_f32 v60, v60, s0
	v_cvt_pk_bf16_f32 v56, v56, s0
	v_cvt_pk_bf16_f32 v52, v52, s0
	v_cvt_pk_bf16_f32 v48, v48, s0
	v_cvt_pk_bf16_f32 v44, v44, s0
	v_cvt_pk_bf16_f32 v40, v40, s0
	v_cvt_pk_bf16_f32 v36, v36, s0
	v_cvt_pk_bf16_f32 v32, v32, s0
	v_cvt_pk_bf16_f32 v28, v28, s0
	v_cvt_pk_bf16_f32 v24, v24, s0
	v_cvt_pk_bf16_f32 v20, v20, s0
	v_cvt_pk_bf16_f32 v16, v16, s0
	v_cvt_pk_bf16_f32 v8, v8, s0
	v_cvt_pk_bf16_f32 v0, v0, s0
	ds_write_b16 v64, v60 offset:33312
	v_max_f32_e32 v60, v63, v63
	ds_write_b16 v64, v56 offset:33344
	v_max_f32_e32 v56, v59, v59
	ds_write_b16 v64, v52 offset:33376
	v_max_f32_e32 v52, v55, v55
	ds_write_b16 v64, v48 offset:33408
	v_max_f32_e32 v48, v51, v51
	ds_write_b16 v64, v44 offset:37664
	v_max_f32_e32 v44, v47, v47
	ds_write_b16 v64, v40 offset:37696
	v_max_f32_e32 v40, v43, v43
	ds_write_b16 v64, v36 offset:37728
	v_max_f32_e32 v36, v39, v39
	ds_write_b16 v64, v32 offset:37760
	v_max_f32_e32 v32, v35, v35
	ds_write_b16 v64, v28 offset:42016
	v_max_f32_e32 v28, v31, v31
	ds_write_b16 v64, v24 offset:42048
	v_max_f32_e32 v24, v27, v27
	ds_write_b16 v64, v20 offset:42080
	v_max_f32_e32 v20, v23, v23
	ds_write_b16 v64, v16 offset:42112
	v_max_f32_e32 v16, v19, v19
	ds_write_b16 v64, v8 offset:46368
	v_max_f32_e32 v8, v11, v11
	ds_write_b16 v64, v0 offset:46464
	v_max_f32_e32 v0, v7, v7
	s_lshl_b64 s[8:9], s[26:27], 13
	v_max_f32_e32 v60, 0, v60
	v_max_f32_e32 v56, 0, v56
	v_max_f32_e32 v52, 0, v52
	v_max_f32_e32 v48, 0, v48
	v_max_f32_e32 v44, 0, v44
	v_max_f32_e32 v40, 0, v40
	v_max_f32_e32 v36, 0, v36
	v_max_f32_e32 v32, 0, v32
	v_max_f32_e32 v28, 0, v28
	v_max_f32_e32 v24, 0, v24
	v_max_f32_e32 v20, 0, v20
	v_max_f32_e32 v16, 0, v16
	v_max_f32_e32 v8, 0, v8
	v_max_f32_e32 v0, 0, v0
	s_add_u32 s14, s44, s8
	v_mul_f32_e32 v60, v60, v60
	v_mul_f32_e32 v56, v56, v56
	v_mul_f32_e32 v52, v52, v52
	v_mul_f32_e32 v48, v48, v48
	v_mul_f32_e32 v44, v44, v44
	v_mul_f32_e32 v40, v40, v40
	v_mul_f32_e32 v36, v36, v36
	v_mul_f32_e32 v32, v32, v32
	v_mul_f32_e32 v28, v28, v28
	v_mul_f32_e32 v24, v24, v24
	v_mul_f32_e32 v20, v20, v20
	v_mul_f32_e32 v16, v16, v16
	v_mul_f32_e32 v8, v8, v8
	v_mul_f32_e32 v0, v0, v0
	s_addc_u32 s15, s45, s9
	s_lshl_b64 s[8:9], s[20:21], 1
	v_cvt_pk_bf16_f32 v60, v60, s0
	v_cvt_pk_bf16_f32 v56, v56, s0
	v_cvt_pk_bf16_f32 v52, v52, s0
	v_cvt_pk_bf16_f32 v48, v48, s0
	v_cvt_pk_bf16_f32 v44, v44, s0
	v_cvt_pk_bf16_f32 v40, v40, s0
	v_cvt_pk_bf16_f32 v36, v36, s0
	v_cvt_pk_bf16_f32 v32, v32, s0
	v_cvt_pk_bf16_f32 v28, v28, s0
	v_cvt_pk_bf16_f32 v24, v24, s0
	v_cvt_pk_bf16_f32 v20, v20, s0
	v_cvt_pk_bf16_f32 v16, v16, s0
	v_cvt_pk_bf16_f32 v8, v8, s0
	v_cvt_pk_bf16_f32 v0, v0, s0
	v_mov_b32_e32 v14, v254
	s_add_u32 s8, s14, s8
	ds_write_b16 v64, v60 offset:33584
	ds_write_b16 v64, v56 offset:33616
	ds_write_b16 v64, v52 offset:33648
	ds_write_b16 v64, v48 offset:33680
	ds_write_b16 v64, v44 offset:37936
	ds_write_b16 v64, v40 offset:37968
	ds_write_b16 v64, v36 offset:38000
	ds_write_b16 v64, v32 offset:38032
	ds_write_b16 v64, v28 offset:42288
	ds_write_b16 v64, v24 offset:42320
	ds_write_b16 v64, v20 offset:42352
	ds_write_b16 v64, v16 offset:42384
	ds_write_b16 v64, v8 offset:46640
	ds_write_b16 v64, v0 offset:46736
	s_waitcnt lgkmcnt(0)
	s_barrier
	s_addc_u32 s9, s15, s9
	v_lshlrev_b32_e32 v0, 4, v14
	v_ashrrev_i32_e32 v4, 4, v14
	v_and_b32_e32 v148, 0xf0, v0
	v_ashrrev_i32_e32 v5, 31, v4
	v_lshl_add_u64 v[8:9], s[8:9], 0, v[148:149]
	v_mad_u64_u32 v[0:1], s[8:9], v4, s42, v[148:149]
	v_lshlrev_b64 v[4:5], 13, v[4:5]
	v_lshl_add_u64 v[10:11], v[8:9], 0, v[4:5]
	v_add_u32_e32 v4, 0x100, v14
	ds_read_b128 v[0:3], v0 offset:32768
	v_ashrrev_i32_e32 v12, 4, v4
	v_mad_u64_u32 v[4:5], s[8:9], v12, s42, v[148:149]
	ds_read_b128 v[4:7], v4 offset:32768
	v_ashrrev_i32_e32 v13, 31, v12
	s_waitcnt lgkmcnt(1)
	global_store_dwordx4 v[10:11], v[0:3], off sc1
	s_and_b64 vcc, exec, s[6:7]
	s_mov_b32 s14, s46
	v_lshlrev_b64 v[0:1], 13, v[12:13]
	v_lshl_add_u64 v[0:1], v[8:9], 0, v[0:1]
	s_waitcnt lgkmcnt(0)
	global_store_dwordx4 v[0:1], v[4:7], off sc1
	v_add_u32_e32 v0, 0x200, v14
	s_nop 0
	v_ashrrev_i32_e32 v4, 4, v0
	v_ashrrev_i32_e32 v5, 31, v4
	v_mad_u64_u32 v[0:1], s[8:9], v4, s42, v[148:149]
	v_lshlrev_b64 v[4:5], 13, v[4:5]
	v_lshl_add_u64 v[10:11], v[8:9], 0, v[4:5]
	v_add_u32_e32 v4, 0x300, v14
	ds_read_b128 v[0:3], v0 offset:32768
	v_ashrrev_i32_e32 v12, 4, v4
	v_mad_u64_u32 v[4:5], s[8:9], v12, s42, v[148:149]
	ds_read_b128 v[4:7], v4 offset:32768
	v_ashrrev_i32_e32 v13, 31, v12
	s_waitcnt lgkmcnt(1)
	global_store_dwordx4 v[10:11], v[0:3], off sc1
	s_nop 1
	v_lshlrev_b64 v[0:1], 13, v[12:13]
	v_lshl_add_u64 v[0:1], v[8:9], 0, v[0:1]
	s_waitcnt lgkmcnt(0)
	global_store_dwordx4 v[0:1], v[4:7], off sc1
	v_add_u32_e32 v0, 0x400, v14
	s_nop 0
	v_ashrrev_i32_e32 v4, 4, v0
	v_ashrrev_i32_e32 v5, 31, v4
	v_mad_u64_u32 v[0:1], s[8:9], v4, s42, v[148:149]
	v_lshlrev_b64 v[4:5], 13, v[4:5]
	v_lshl_add_u64 v[10:11], v[8:9], 0, v[4:5]
	v_add_u32_e32 v4, 0x500, v14
	ds_read_b128 v[0:3], v0 offset:32768
	v_ashrrev_i32_e32 v12, 4, v4
	v_mad_u64_u32 v[4:5], s[8:9], v12, s42, v[148:149]
	ds_read_b128 v[4:7], v4 offset:32768
	v_ashrrev_i32_e32 v13, 31, v12
	s_waitcnt lgkmcnt(1)
	global_store_dwordx4 v[10:11], v[0:3], off sc1
	s_nop 1
	v_lshlrev_b64 v[0:1], 13, v[12:13]
	v_lshl_add_u64 v[0:1], v[8:9], 0, v[0:1]
	s_waitcnt lgkmcnt(0)
	global_store_dwordx4 v[0:1], v[4:7], off sc1
	v_add_u32_e32 v0, 0x600, v14
	s_nop 0
	v_ashrrev_i32_e32 v4, 4, v0
	v_ashrrev_i32_e32 v5, 31, v4
	v_mad_u64_u32 v[0:1], s[8:9], v4, s42, v[148:149]
	v_lshlrev_b64 v[4:5], 13, v[4:5]
	v_lshl_add_u64 v[10:11], v[8:9], 0, v[4:5]
	v_add_u32_e32 v4, 0x700, v14
	ds_read_b128 v[0:3], v0 offset:32768
	v_ashrrev_i32_e32 v12, 4, v4
	v_mad_u64_u32 v[4:5], s[8:9], v12, s42, v[148:149]
	ds_read_b128 v[4:7], v4 offset:32768
	v_ashrrev_i32_e32 v13, 31, v12
	s_waitcnt lgkmcnt(1)
	global_store_dwordx4 v[10:11], v[0:3], off sc1
	s_mov_b64 s[8:9], -1
	s_nop 0
	v_lshlrev_b64 v[0:1], 13, v[12:13]
	v_lshl_add_u64 v[0:1], v[8:9], 0, v[0:1]
	s_waitcnt lgkmcnt(0)
	global_store_dwordx4 v[0:1], v[4:7], off sc1
	s_cbranch_vccnz .LBB0_199

.LBB0_181:
	v_mov_b32_e32 v0, v84
	v_cmp_gt_i32_e32 vcc, 8, v0
	v_mov_b32_e32 v1, -1
	s_or_b64 s[22:23], s[22:23], exec
	s_and_saveexec_b64 s[28:29], vcc
	s_cbranch_execz .LBB0_180
	v_add_u32_e32 v1, s2, v0
	v_and_b32_e32 v1, 7, v1
	s_cmp_eq_u32 s100, 1
	s_cbranch_scc1 .Lpp1_use
	v_lshlrev_b32_e32 v3, 6, v1
	global_atomic_add v3, v3, v159, s[12:13] sc0
	s_branch .Lpp1_join
.Lpp1_use:
	s_waitcnt vmcnt(0)
	v_mov_b32_e32 v3, v253
	s_mov_b32 s100, 0
.Lpp1_join:
	v_mad_u32_u24 v2, v1, s89, s89
	v_lshrrev_b32_e32 v2, 3, v2
	s_andn2_b64 s[16:17], s[22:23], exec
	v_add_u32_e32 v84, 1, v0
	s_waitcnt vmcnt(0)
	v_mad_u32_u24 v1, v1, s92, v3
	v_cmp_lt_i32_e32 vcc, v1, v2
	s_and_b64 s[22:23], vcc, exec
	s_or_b64 s[22:23], s[16:17], s[22:23]
	s_branch .LBB0_180
